# in-proj row-scale loop: reuse the previous iteration's scale when the unit has the same row tile (2 loads instead of 6-7)
# speedup vs baseline: 1.0053x; 1.0053x over previous
.LBB0_596:
	s_or_b64 exec, exec, s[4:5]
	s_mov_b32 s45, s72
	s_mov_b32 s16, s71
	v_mbcnt_lo_u32_b32 v0, -1, 0
	v_mbcnt_hi_u32_b32 v0, -1, v0
	s_getreg_b32 s2, hwreg(HW_REG_HW_ID, 0, 6)
	s_lshl_b32 s2, s2, 2
	s_and_b32 s2, s2, 0xfc
	s_add_i32 s2, s2, 0
	s_add_i32 s2, s2, 0x23400
	v_mov_b32_e32 v2, s2
	ds_read_b32 v2, v2
	v_and_b32_e32 v6, 1, v0
	s_ashr_i32 s17, s16, 31
	s_ashr_i32 s46, s45, 31
	v_cmp_eq_u32_e64 s[4:5], 0, v6
	s_waitcnt lgkmcnt(0)
	v_readfirstlane_b32 s2, v2
	s_mov_b64 s[6:7], s[16:17]
	s_nop 0
	v_lshl_add_u32 v2, s2, 6, v0
	v_ashrrev_i32_e32 v4, 1, v2
	v_ashrrev_i32_e32 v5, 31, v4
	v_lshlrev_b64 v[2:3], 7, v[4:5]
	v_lshl_add_u64 v[2:3], s[12:13], 0, v[2:3]
	v_lshlrev_b32_e32 v0, 6, v6
	v_lshl_add_u64 v[2:3], v[2:3], 0, v[0:1]
	s_mov_b64 s[2:3], 0x100000
	v_lshl_add_u64 v[2:3], v[2:3], 0, s[2:3]
	v_readlane_b32 s2, v255, 4
	s_nop 1
	v_lshl_add_u32 v0, v4, 2, s2
	s_mov_b32 s100, -1
	s_branch .LBB0_599

.LBB0_599:
	v_cmp_gt_i64_e32 vcc, s[6:7], v[170:171]
	s_mov_b64 s[8:9], -1
	s_cbranch_vccnz .LBB0_598
	s_ashr_i32 s2, s6, 31
	s_lshr_b32 s2, s2, 29
	s_add_i32 s2, s6, s2
	s_ashr_i32 s3, s2, 3
	s_and_b32 s2, s2, -8
	s_sub_i32 s2, s6, s2
	s_cmp_lt_i32 s2, 0
	s_cselect_b32 s8, s77, 0xd0
	s_mul_i32 s2, s2, s8
	s_add_i32 s2, s2, s3
	s_mul_hi_i32 s3, s2, 0x4ec4ec4f
	s_lshr_b32 s8, s3, 31
	s_ashr_i32 s3, s3, 5
	s_add_i32 s3, s3, s8
	s_lshl_b32 s8, s3, 3
	s_sub_i32 s9, 0x80, s8
	s_min_i32 s9, s9, 8
	s_abs_i32 s9, s9
	v_cvt_f32_u32_e32 v4, s9
	s_sub_i32 s10, 0, s9
	s_mulk_i32 s3, 0x68
	s_sub_i32 s2, s2, s3
	v_rcp_iflag_f32_e32 v4, v4
	s_ashr_i32 s3, s2, 31
	s_abs_i32 s2, s2
	v_mul_f32_e32 v4, 0x4f7ffffe, v4
	v_cvt_u32_f32_e32 v4, v4
	s_nop 0
	v_readfirstlane_b32 s11, v4
	s_mul_i32 s10, s10, s11
	s_mul_hi_u32 s10, s11, s10
	s_add_i32 s11, s11, s10
	s_mul_hi_u32 s10, s2, s11
	s_mul_i32 s10, s10, s9
	s_sub_i32 s2, s2, s10
	s_sub_i32 s10, s2, s9
	s_cmp_ge_u32 s2, s9
	s_cselect_b32 s2, s10, s2
	s_sub_i32 s10, s2, s9
	s_cmp_ge_u32 s2, s9
	s_cselect_b32 s2, s10, s2
	s_xor_b32 s2, s2, s3
	s_sub_i32 s2, s2, s3
	s_add_i32 s2, s8, s2
	s_ashr_i32 s3, s2, 31
	s_lshl_b64 s[2:3], s[2:3], 15
	s_cmp_eq_u32 s2, s100
	s_cbranch_scc1 .Lrsip_same
	s_mov_b32 s100, s2
	v_lshl_add_u64 v[16:17], v[2:3], 0, s[2:3]
	s_waitcnt lgkmcnt(0)
	global_load_dwordx4 v[4:7], v[16:17], off
	global_load_dwordx4 v[8:11], v[16:17], off offset:16
	global_load_dwordx4 v[12:15], v[16:17], off offset:32
	s_nop 0
	global_load_dwordx4 v[16:19], v[16:17], off offset:48
	s_waitcnt vmcnt(3)
	v_add_f32_e32 v4, v4, v5
	v_add_f32_e32 v5, v6, v7
	s_waitcnt vmcnt(2)
	v_add_f32_e32 v6, v8, v9
	v_add_f32_e32 v7, v10, v11
	s_waitcnt vmcnt(1)
	v_add_f32_e32 v8, v12, v13
	v_add_f32_e32 v9, v14, v15
	v_add_f32_e32 v4, v4, v5
	v_add_f32_e32 v5, v6, v7
	s_waitcnt vmcnt(0)
	v_add_f32_e32 v10, v16, v17
	v_add_f32_e32 v11, v18, v19
	v_add_f32_e32 v6, v8, v9
	v_add_f32_e32 v4, v4, v5
	v_add_f32_e32 v4, v4, v6
	v_add_f32_e32 v5, v10, v11
	v_add_f32_e32 v4, v4, v5
	ds_swizzle_b32 v5, v4 offset:swizzle(SWAP,1)
	s_and_saveexec_b64 s[8:9], s[4:5]
	s_cbranch_execz .LBB0_597
	s_waitcnt lgkmcnt(0)
	v_add_f32_e32 v4, v4, v5
	v_fmamk_f32 v4, v4, 0x3a800000, v220
	v_mul_f32_e32 v5, 0x4b800000, v4
	v_cmp_gt_f32_e32 vcc, s33, v4
	s_nop 1
	v_cndmask_b32_e32 v4, v4, v5, vcc
	v_rsq_f32_e32 v4, v4
	s_nop 0
	v_mul_f32_e32 v5, 0x45800000, v4
	v_cndmask_b32_e32 v4, v4, v5, vcc
	v_mov_b32_e32 v20, v4
	ds_write_b32 v0, v4
	s_branch .LBB0_597
.Lrsip_same:
	s_and_saveexec_b64 s[8:9], s[4:5]
	ds_write_b32 v0, v20
	s_branch .LBB0_597
